# one static s_setprio 1 for waves 4-7 at kernel entry, per-segment flips deleted
# baseline (speedup 1.0000x reference)
; #define LAS __attribute__((address_space(3)))
; #define MY_LANE() ((int)__builtin_amdgcn_mbcnt_hi(~0u, __builtin_amdgcn_mbcnt_lo(~0u, 0u)))
; #define MY_TID() (wave_id * 64 + MY_LANE())
; __global__ void __launch_bounds__(NTHREADS, 2) trunk_fwd(Args a) {
;     extern __shared__ __attribute__((aligned(16))) unsigned char lds_raw[];
;     cg::grid_group grid = cg::this_grid();
;     LAS unsigned char* lds = (LAS unsigned char*)lds_raw;
;     LAS float* rs = (LAS float*)(lds + LDS_RS);
;     const int G = gridDim.x, w = blockIdx.x, NGW = G * NWAVES;
;     if (a.ws == nullptr) grid.sync();
;     const int wave_id = __builtin_amdgcn_readfirstlane((int)threadIdx.x >> 6);
;     ...
;     volatile LAS unsigned* bst = (volatile LAS unsigned*)(lds + LDS_RS + 1024);
;     if (MY_TID() < 4) bst[MY_TID()] = 0u;
;     __syncthreads();
;     const XcdBarrier xbar = xcd_barrier_post((unsigned*)a.ws + CW_BAR, bst, wave_id == 0 && MY_LANE() == 0);
_Z9trunk_fwd4Args:
	v_readfirstlane_b32 s3, v0
	s_nop 3
	s_and_b32 s3, s3, 0x3ff
	s_lshr_b32 s3, s3, 6
	s_cmp_ge_u32 s3, 4
	s_cbranch_scc0 .Lprio_done
	s_setprio 1
.Lprio_done:
	s_load_dwordx4 s[60:63], s[0:1], 0x60
	s_load_dwordx8 s[4:11], s[0:1], 0x40
	s_load_dwordx2 s[88:89], s[0:1], 0x70
	s_mov_b32 s96, s2
	s_waitcnt lgkmcnt(0)
	v_writelane_b32 v253, s4, 0
	s_nop 1
	v_writelane_b32 v253, s5, 1
	v_writelane_b32 v253, s6, 2
	v_writelane_b32 v253, s7, 3
	v_writelane_b32 v253, s8, 4
	v_writelane_b32 v253, s9, 5
	v_writelane_b32 v253, s10, 6
	v_writelane_b32 v253, s11, 7
	s_add_u32 s6, s0, 0x70
	s_addc_u32 s7, s1, 0
	s_cmp_eq_u64 s[62:63], 0
	s_mov_b64 s[4:5], 0
	s_cbranch_scc1 .LBB0_2
	v_and_b32_e32 v1, 0x3ff, v0
	s_load_dword s2, s[0:1], 0x78
	s_andn2_b64 vcc, exec, s[4:5]
	s_cbranch_vccz .LBB0_3
	s_branch .LBB0_14
